# P6 mid-epilogue: graduated vmcnt waits on the two 8-load gate batches instead of vmcnt(0)
# speedup vs baseline: 1.0023x; 1.0009x over previous
.LBB0_667:
	v_mov_b32_e32 v1, v194
	v_mov_b32_e32 v2, v195
	s_and_b64 vcc, exec, s[6:7]
	v_lshl_add_u32 v2, v2, 3, s93
	v_add_u32_e32 v152, s51, v1
	v_ashrrev_i32_e32 v3, 31, v2
	v_lshlrev_b64 v[2:3], 1, v[2:3]
	v_ashrrev_i32_e32 v153, 31, v152
	v_lshl_add_u64 v[154:155], s[30:31], 0, v[2:3]
	v_lshlrev_b64 v[132:133], 12, v[152:153]
	v_lshl_add_u64 v[132:133], v[154:155], 0, v[132:133]
	global_load_dwordx4 v[160:163], v[132:133], off offset:2048
	global_load_dwordx4 v[164:167], v[132:133], off offset:2304
	v_add_u32_e32 v172, 16, v152
	v_add_u32_e32 v158, 32, v152
	v_add_u32_e32 v156, 48, v152
	v_ashrrev_i32_e32 v173, 31, v172
	v_ashrrev_i32_e32 v159, 31, v158
	v_ashrrev_i32_e32 v157, 31, v156
	v_lshlrev_b64 v[134:135], 12, v[172:173]
	v_lshlrev_b64 v[136:137], 12, v[158:159]
	v_lshlrev_b64 v[132:133], 11, v[152:153]
	v_lshl_add_u64 v[2:3], s[22:23], 0, v[2:3]
	v_lshlrev_b64 v[138:139], 12, v[156:157]
	v_lshl_add_u64 v[134:135], v[154:155], 0, v[134:135]
	v_lshl_add_u64 v[136:137], v[154:155], 0, v[136:137]
	v_lshl_add_u64 v[174:175], v[154:155], 0, v[138:139]
	v_lshl_add_u64 v[176:177], v[2:3], 0, v[132:133]
	global_load_dwordx4 v[168:171], v[134:135], off offset:2048
	global_load_dwordx4 v[148:151], v[134:135], off offset:2304
	global_load_dwordx4 v[144:147], v[136:137], off offset:2048
	global_load_dwordx4 v[140:143], v[136:137], off offset:2304
	s_nop 0
	global_load_dwordx4 v[136:139], v[174:175], off offset:2048
	global_load_dwordx4 v[132:135], v[174:175], off offset:2304
	s_mov_b32 s64, s92
	s_mov_b32 s12, s50
	s_mov_b64 s[58:59], s[56:57]
	s_mov_b64 s[60:61], s[52:53]
	s_mov_b64 s[62:63], s[54:55]
	s_waitcnt vmcnt(7)
	v_lshlrev_b32_e32 v1, 16, v160
	v_and_b32_e32 v153, 0xffff0000, v160
	v_mul_f32_e32 v1, 0xbfb8aa3b, v1
	v_mul_f32_e32 v153, 0xbfb8aa3b, v153
	v_exp_f32_e32 v1, v1
	v_exp_f32_e32 v153, v153
	v_lshlrev_b32_e32 v160, 16, v161
	v_and_b32_e32 v161, 0xffff0000, v161
	v_lshlrev_b32_e32 v174, 16, v162
	v_and_b32_e32 v162, 0xffff0000, v162
	v_lshlrev_b32_e32 v175, 16, v163
	v_and_b32_e32 v163, 0xffff0000, v163
	v_mul_f32_e32 v160, 0xbfb8aa3b, v160
	v_mul_f32_e32 v161, 0xbfb8aa3b, v161
	v_mul_f32_e32 v174, 0xbfb8aa3b, v174
	v_mul_f32_e32 v162, 0xbfb8aa3b, v162
	v_mul_f32_e32 v163, 0xbfb8aa3b, v163
	v_exp_f32_e32 v160, v160
	v_exp_f32_e32 v161, v161
	v_add_f32_e32 v1, 1.0, v1
	v_add_f32_e32 v153, 1.0, v153
	v_mul_f32_e32 v175, 0xbfb8aa3b, v175
	v_exp_f32_e32 v174, v174
	v_exp_f32_e32 v162, v162
	v_exp_f32_e32 v163, v163
	v_rcp_f32_e32 v1, v1
	v_rcp_f32_e32 v153, v153
	v_exp_f32_e32 v175, v175
	v_add_f32_e32 v160, 1.0, v160
	v_add_f32_e32 v161, 1.0, v161
	s_waitcnt vmcnt(6)
	v_lshlrev_b32_e32 v178, 16, v164
	v_and_b32_e32 v164, 0xffff0000, v164
	v_lshlrev_b32_e32 v198, 16, v166
	v_add_f32_e32 v174, 1.0, v174
	v_add_f32_e32 v162, 1.0, v162
	v_add_f32_e32 v163, 1.0, v163
	v_rcp_f32_e32 v160, v160
	v_rcp_f32_e32 v161, v161
	v_mul_f32_e32 v1, v124, v1
	v_mul_f32_e32 v124, v125, v153
	v_mul_f32_e32 v178, 0xbfb8aa3b, v178
	v_mul_f32_e32 v198, 0xbfb8aa3b, v198
	v_add_f32_e32 v175, 1.0, v175
	v_rcp_f32_e32 v174, v174
	v_rcp_f32_e32 v162, v162
	v_rcp_f32_e32 v163, v163
	v_cvt_pk_bf16_f32 v124, v1, v124
	v_mul_f32_e32 v1, 0xbfb8aa3b, v164
	v_exp_f32_e32 v178, v178
	v_exp_f32_e32 v198, v198
	v_rcp_f32_e32 v175, v175
	v_exp_f32_e32 v1, v1
	v_mul_f32_e32 v125, v126, v160
	v_mul_f32_e32 v126, v127, v161
	v_and_b32_e32 v166, 0xffff0000, v166
	v_mul_f32_e32 v128, v128, v174
	v_mul_f32_e32 v129, v129, v162
	v_mul_f32_e32 v127, v131, v163
	v_cvt_pk_bf16_f32 v125, v125, v126
	v_cvt_pk_bf16_f32 v126, v128, v129
	v_add_f32_e32 v178, 1.0, v178
	v_mul_f32_e32 v130, v130, v175
	v_cvt_pk_bf16_f32 v127, v130, v127
	global_store_dwordx4 v[176:177], v[124:127], off
	v_add_f32_e32 v1, 1.0, v1
	v_rcp_f32_e32 v1, v1
	v_add_f32_e32 v125, 1.0, v198
	v_mul_f32_e32 v126, 0xbfb8aa3b, v166
	v_rcp_f32_e32 v124, v178
	v_rcp_f32_e32 v125, v125
	v_exp_f32_e32 v126, v126
	v_lshlrev_b32_e32 v179, 16, v165
	v_lshlrev_b32_e32 v199, 16, v167
	v_mul_f32_e32 v116, v116, v124
	v_mul_f32_e32 v120, v120, v125
	v_mul_f32_e32 v1, v117, v1
	v_add_f32_e32 v117, 1.0, v126
	v_mul_f32_e32 v124, 0xbfb8aa3b, v179
	v_mul_f32_e32 v125, 0xbfb8aa3b, v199
	v_rcp_f32_e32 v117, v117
	v_exp_f32_e32 v124, v124
	v_exp_f32_e32 v125, v125
	v_and_b32_e32 v165, 0xffff0000, v165
	v_and_b32_e32 v167, 0xffff0000, v167
	v_mul_f32_e32 v121, v121, v117
	v_add_f32_e32 v117, 1.0, v124
	v_add_f32_e32 v124, 1.0, v125
	v_mul_f32_e32 v125, 0xbfb8aa3b, v165
	v_exp_f32_e32 v125, v125
	v_mul_f32_e32 v126, 0xbfb8aa3b, v167
	v_exp_f32_e32 v126, v126
	v_rcp_f32_e32 v117, v117
	v_add_f32_e32 v125, 1.0, v125
	v_rcp_f32_e32 v125, v125
	v_add_f32_e32 v126, 1.0, v126
	v_rcp_f32_e32 v126, v126
	v_rcp_f32_e32 v124, v124
	v_mul_f32_e32 v117, v118, v117
	v_mul_f32_e32 v118, v119, v125
	v_mul_f32_e32 v119, v123, v126
	v_cvt_pk_bf16_f32 v116, v116, v1
	v_cvt_pk_bf16_f32 v117, v117, v118
	v_cvt_pk_bf16_f32 v118, v120, v121
	v_mul_f32_e32 v122, v122, v124
	v_cvt_pk_bf16_f32 v119, v122, v119
	global_store_dwordx4 v[176:177], v[116:119], off offset:256
	s_waitcnt vmcnt(7)
	v_lshlrev_b32_e32 v1, 16, v168
	v_mul_f32_e32 v1, 0xbfb8aa3b, v1
	v_and_b32_e32 v118, 0xffff0000, v168
	v_mul_f32_e32 v118, 0xbfb8aa3b, v118
	v_exp_f32_e32 v1, v1
	v_exp_f32_e32 v118, v118
	v_and_b32_e32 v122, 0xffff0000, v170
	v_mul_f32_e32 v122, 0xbfb8aa3b, v122
	v_add_f32_e32 v1, 1.0, v1
	v_add_f32_e32 v118, 1.0, v118
	v_rcp_f32_e32 v1, v1
	v_rcp_f32_e32 v118, v118
	v_exp_f32_e32 v122, v122
	v_lshlrev_b32_e32 v119, 16, v169
	v_lshlrev_b32_e32 v123, 16, v171
	v_mul_f32_e32 v1, v108, v1
	v_mul_f32_e32 v108, v109, v118
	v_add_f32_e32 v109, 1.0, v122
	v_mul_f32_e32 v118, 0xbfb8aa3b, v119
	v_mul_f32_e32 v119, 0xbfb8aa3b, v123
	v_rcp_f32_e32 v109, v109
	v_exp_f32_e32 v118, v118
	v_exp_f32_e32 v119, v119
	v_and_b32_e32 v120, 0xffff0000, v169
	v_and_b32_e32 v124, 0xffff0000, v171
	v_lshlrev_b32_e32 v121, 16, v170
	v_mul_f32_e32 v113, v113, v109
	v_add_f32_e32 v109, 1.0, v118
	v_add_f32_e32 v118, 1.0, v119
	v_mul_f32_e32 v119, 0xbfb8aa3b, v120
	v_mul_f32_e32 v120, 0xbfb8aa3b, v124
	v_mul_f32_e32 v121, 0xbfb8aa3b, v121
	v_exp_f32_e32 v119, v119
	v_exp_f32_e32 v120, v120
	v_exp_f32_e32 v121, v121
	v_rcp_f32_e32 v109, v109
	v_add_f32_e32 v119, 1.0, v119
	v_add_f32_e32 v120, 1.0, v120
	v_add_f32_e32 v121, 1.0, v121
	v_rcp_f32_e32 v119, v119
	v_rcp_f32_e32 v120, v120
	v_rcp_f32_e32 v121, v121
	v_rcp_f32_e32 v118, v118
	v_lshlrev_b64 v[116:117], 11, v[172:173]
	v_lshl_add_u64 v[116:117], v[2:3], 0, v[116:117]
	v_mul_f32_e32 v109, v110, v109
	v_mul_f32_e32 v110, v111, v119
	v_mul_f32_e32 v111, v115, v120
	v_cvt_pk_bf16_f32 v108, v1, v108
	v_mul_f32_e32 v112, v112, v121
	v_mul_f32_e32 v114, v114, v118
	v_cvt_pk_bf16_f32 v109, v109, v110
	v_cvt_pk_bf16_f32 v110, v112, v113
	v_cvt_pk_bf16_f32 v111, v114, v111
	global_store_dwordx4 v[116:117], v[108:111], off
	s_waitcnt vmcnt(7)
	v_lshlrev_b32_e32 v1, 16, v148
	v_mul_f32_e32 v1, 0xbfb8aa3b, v1
	v_and_b32_e32 v108, 0xffff0000, v148
	v_mul_f32_e32 v108, 0xbfb8aa3b, v108
	v_exp_f32_e32 v1, v1
	v_exp_f32_e32 v108, v108
	v_and_b32_e32 v112, 0xffff0000, v150
	v_mul_f32_e32 v112, 0xbfb8aa3b, v112
	v_add_f32_e32 v1, 1.0, v1
	v_add_f32_e32 v108, 1.0, v108
	v_rcp_f32_e32 v1, v1
	v_rcp_f32_e32 v108, v108
	v_exp_f32_e32 v112, v112
	v_lshlrev_b32_e32 v109, 16, v149
	v_lshlrev_b32_e32 v113, 16, v151
	v_mul_f32_e32 v1, v100, v1
	v_mul_f32_e32 v100, v101, v108
	v_add_f32_e32 v101, 1.0, v112
	v_mul_f32_e32 v108, 0xbfb8aa3b, v109
	v_mul_f32_e32 v109, 0xbfb8aa3b, v113
	v_rcp_f32_e32 v101, v101
	v_exp_f32_e32 v108, v108
	v_exp_f32_e32 v109, v109
	v_and_b32_e32 v110, 0xffff0000, v149
	v_lshlrev_b32_e32 v111, 16, v150
	v_and_b32_e32 v114, 0xffff0000, v151
	v_mul_f32_e32 v105, v105, v101
	v_add_f32_e32 v101, 1.0, v108
	v_add_f32_e32 v108, 1.0, v109
	v_mul_f32_e32 v109, 0xbfb8aa3b, v110
	v_mul_f32_e32 v111, 0xbfb8aa3b, v111
	v_exp_f32_e32 v109, v109
	v_mul_f32_e32 v110, 0xbfb8aa3b, v114
	v_exp_f32_e32 v111, v111
	v_exp_f32_e32 v110, v110
	v_add_f32_e32 v109, 1.0, v109
	v_rcp_f32_e32 v101, v101
	v_add_f32_e32 v111, 1.0, v111
	v_rcp_f32_e32 v109, v109
	v_add_f32_e32 v110, 1.0, v110
	v_rcp_f32_e32 v111, v111
	v_rcp_f32_e32 v110, v110
	v_rcp_f32_e32 v108, v108
	v_mul_f32_e32 v101, v102, v101
	v_mul_f32_e32 v102, v103, v109
	v_mul_f32_e32 v104, v104, v111
	v_mul_f32_e32 v103, v107, v110
	v_cvt_pk_bf16_f32 v100, v1, v100
	v_cvt_pk_bf16_f32 v101, v101, v102
	v_cvt_pk_bf16_f32 v102, v104, v105
	v_mul_f32_e32 v106, v106, v108
	v_cvt_pk_bf16_f32 v103, v106, v103
	global_store_dwordx4 v[116:117], v[100:103], off offset:256
	s_waitcnt vmcnt(7)
	v_lshlrev_b32_e32 v1, 16, v144
	v_mul_f32_e32 v1, 0xbfb8aa3b, v1
	v_and_b32_e32 v102, 0xffff0000, v144
	v_mul_f32_e32 v102, 0xbfb8aa3b, v102
	v_exp_f32_e32 v1, v1
	v_exp_f32_e32 v102, v102
	v_and_b32_e32 v106, 0xffff0000, v146
	v_mul_f32_e32 v106, 0xbfb8aa3b, v106
	v_add_f32_e32 v1, 1.0, v1
	v_add_f32_e32 v102, 1.0, v102
	v_rcp_f32_e32 v1, v1
	v_rcp_f32_e32 v102, v102
	v_exp_f32_e32 v106, v106
	v_lshlrev_b32_e32 v103, 16, v145
	v_lshlrev_b32_e32 v107, 16, v147
	v_mul_f32_e32 v1, v92, v1
	v_mul_f32_e32 v92, v93, v102
	v_add_f32_e32 v93, 1.0, v106
	v_mul_f32_e32 v102, 0xbfb8aa3b, v103
	v_mul_f32_e32 v103, 0xbfb8aa3b, v107
	v_rcp_f32_e32 v93, v93
	v_exp_f32_e32 v102, v102
	v_exp_f32_e32 v103, v103
	v_and_b32_e32 v104, 0xffff0000, v145
	v_and_b32_e32 v108, 0xffff0000, v147
	v_lshlrev_b32_e32 v105, 16, v146
	v_mul_f32_e32 v97, v97, v93
	v_add_f32_e32 v93, 1.0, v102
	v_add_f32_e32 v102, 1.0, v103
	v_mul_f32_e32 v103, 0xbfb8aa3b, v104
	v_mul_f32_e32 v104, 0xbfb8aa3b, v108
	v_mul_f32_e32 v105, 0xbfb8aa3b, v105
	v_exp_f32_e32 v103, v103
	v_exp_f32_e32 v104, v104
	v_exp_f32_e32 v105, v105
	v_rcp_f32_e32 v93, v93
	v_add_f32_e32 v103, 1.0, v103
	v_add_f32_e32 v104, 1.0, v104
	v_add_f32_e32 v105, 1.0, v105
	v_rcp_f32_e32 v103, v103
	v_rcp_f32_e32 v104, v104
	v_rcp_f32_e32 v105, v105
	v_rcp_f32_e32 v102, v102
	v_lshlrev_b64 v[100:101], 11, v[158:159]
	v_lshl_add_u64 v[100:101], v[2:3], 0, v[100:101]
	v_mul_f32_e32 v93, v94, v93
	v_mul_f32_e32 v94, v95, v103
	v_mul_f32_e32 v95, v99, v104
	v_cvt_pk_bf16_f32 v92, v1, v92
	v_mul_f32_e32 v96, v96, v105
	v_mul_f32_e32 v98, v98, v102
	v_cvt_pk_bf16_f32 v93, v93, v94
	v_cvt_pk_bf16_f32 v94, v96, v97
	v_cvt_pk_bf16_f32 v95, v98, v95
	global_store_dwordx4 v[100:101], v[92:95], off
	s_waitcnt vmcnt(7)
	v_lshlrev_b32_e32 v1, 16, v140
	v_mul_f32_e32 v1, 0xbfb8aa3b, v1
	v_and_b32_e32 v92, 0xffff0000, v140
	v_mul_f32_e32 v92, 0xbfb8aa3b, v92
	v_exp_f32_e32 v1, v1
	v_exp_f32_e32 v92, v92
	v_and_b32_e32 v96, 0xffff0000, v142
	v_mul_f32_e32 v96, 0xbfb8aa3b, v96
	v_add_f32_e32 v1, 1.0, v1
	v_add_f32_e32 v92, 1.0, v92
	v_rcp_f32_e32 v1, v1
	v_rcp_f32_e32 v92, v92
	v_exp_f32_e32 v96, v96
	v_lshlrev_b32_e32 v93, 16, v141
	v_lshlrev_b32_e32 v97, 16, v143
	v_mul_f32_e32 v1, v84, v1
	v_mul_f32_e32 v84, v85, v92
	v_add_f32_e32 v85, 1.0, v96
	v_mul_f32_e32 v92, 0xbfb8aa3b, v93
	v_mul_f32_e32 v93, 0xbfb8aa3b, v97
	v_rcp_f32_e32 v85, v85
	v_exp_f32_e32 v92, v92
	v_exp_f32_e32 v93, v93
	v_and_b32_e32 v94, 0xffff0000, v141
	v_lshlrev_b32_e32 v95, 16, v142
	v_and_b32_e32 v98, 0xffff0000, v143
	v_mul_f32_e32 v89, v89, v85
	v_add_f32_e32 v85, 1.0, v92
	v_add_f32_e32 v92, 1.0, v93
	v_mul_f32_e32 v93, 0xbfb8aa3b, v94
	v_mul_f32_e32 v95, 0xbfb8aa3b, v95
	v_exp_f32_e32 v93, v93
	v_mul_f32_e32 v94, 0xbfb8aa3b, v98
	v_exp_f32_e32 v95, v95
	v_exp_f32_e32 v94, v94
	v_add_f32_e32 v93, 1.0, v93
	v_rcp_f32_e32 v85, v85
	v_add_f32_e32 v95, 1.0, v95
	v_rcp_f32_e32 v93, v93
	v_add_f32_e32 v94, 1.0, v94
	v_rcp_f32_e32 v95, v95
	v_rcp_f32_e32 v94, v94
	v_rcp_f32_e32 v92, v92
	v_mul_f32_e32 v85, v86, v85
	v_mul_f32_e32 v86, v87, v93
	v_mul_f32_e32 v88, v88, v95
	v_mul_f32_e32 v87, v91, v94
	v_cvt_pk_bf16_f32 v84, v1, v84
	v_cvt_pk_bf16_f32 v85, v85, v86
	v_cvt_pk_bf16_f32 v86, v88, v89
	v_mul_f32_e32 v90, v90, v92
	v_cvt_pk_bf16_f32 v87, v90, v87
	global_store_dwordx4 v[100:101], v[84:87], off offset:256
	s_waitcnt vmcnt(7)
	v_lshlrev_b32_e32 v1, 16, v136
	v_mul_f32_e32 v1, 0xbfb8aa3b, v1
	v_and_b32_e32 v86, 0xffff0000, v136
	v_mul_f32_e32 v86, 0xbfb8aa3b, v86
	v_exp_f32_e32 v1, v1
	v_exp_f32_e32 v86, v86
	v_and_b32_e32 v90, 0xffff0000, v138
	v_mul_f32_e32 v90, 0xbfb8aa3b, v90
	v_add_f32_e32 v1, 1.0, v1
	v_add_f32_e32 v86, 1.0, v86
	v_rcp_f32_e32 v1, v1
	v_rcp_f32_e32 v86, v86
	v_exp_f32_e32 v90, v90
	v_lshlrev_b32_e32 v87, 16, v137
	v_lshlrev_b32_e32 v91, 16, v139
	v_mul_f32_e32 v1, v76, v1
	v_mul_f32_e32 v76, v77, v86
	v_add_f32_e32 v77, 1.0, v90
	v_mul_f32_e32 v86, 0xbfb8aa3b, v87
	v_mul_f32_e32 v87, 0xbfb8aa3b, v91
	v_rcp_f32_e32 v77, v77
	v_exp_f32_e32 v86, v86
	v_exp_f32_e32 v87, v87
	v_and_b32_e32 v88, 0xffff0000, v137
	v_and_b32_e32 v92, 0xffff0000, v139
	v_lshlrev_b32_e32 v89, 16, v138
	v_mul_f32_e32 v81, v81, v77
	v_add_f32_e32 v77, 1.0, v86
	v_add_f32_e32 v86, 1.0, v87
	v_mul_f32_e32 v87, 0xbfb8aa3b, v88
	v_mul_f32_e32 v88, 0xbfb8aa3b, v92
	v_mul_f32_e32 v89, 0xbfb8aa3b, v89
	v_exp_f32_e32 v87, v87
	v_exp_f32_e32 v88, v88
	v_exp_f32_e32 v89, v89
	v_rcp_f32_e32 v77, v77
	v_add_f32_e32 v87, 1.0, v87
	v_add_f32_e32 v88, 1.0, v88
	v_add_f32_e32 v89, 1.0, v89
	v_rcp_f32_e32 v87, v87
	v_rcp_f32_e32 v88, v88
	v_rcp_f32_e32 v89, v89
	v_rcp_f32_e32 v86, v86
	v_lshlrev_b64 v[84:85], 11, v[156:157]
	v_lshl_add_u64 v[84:85], v[2:3], 0, v[84:85]
	v_mul_f32_e32 v77, v78, v77
	v_mul_f32_e32 v78, v79, v87
	v_mul_f32_e32 v79, v83, v88
	v_cvt_pk_bf16_f32 v76, v1, v76
	v_mul_f32_e32 v80, v80, v89
	v_mul_f32_e32 v82, v82, v86
	v_cvt_pk_bf16_f32 v77, v77, v78
	v_cvt_pk_bf16_f32 v78, v80, v81
	v_cvt_pk_bf16_f32 v79, v82, v79
	global_store_dwordx4 v[84:85], v[76:79], off
	s_waitcnt vmcnt(7)
	v_lshlrev_b32_e32 v1, 16, v132
	v_mul_f32_e32 v1, 0xbfb8aa3b, v1
	v_and_b32_e32 v76, 0xffff0000, v132
	v_mul_f32_e32 v76, 0xbfb8aa3b, v76
	v_exp_f32_e32 v1, v1
	v_exp_f32_e32 v76, v76
	v_and_b32_e32 v80, 0xffff0000, v134
	v_mul_f32_e32 v80, 0xbfb8aa3b, v80
	v_add_f32_e32 v1, 1.0, v1
	v_add_f32_e32 v76, 1.0, v76
	v_rcp_f32_e32 v1, v1
	v_rcp_f32_e32 v76, v76
	v_exp_f32_e32 v80, v80
	v_lshlrev_b32_e32 v77, 16, v133
	v_lshlrev_b32_e32 v81, 16, v135
	v_mul_f32_e32 v1, v68, v1
	v_mul_f32_e32 v68, v69, v76
	v_add_f32_e32 v69, 1.0, v80
	v_mul_f32_e32 v76, 0xbfb8aa3b, v77
	v_mul_f32_e32 v77, 0xbfb8aa3b, v81
	v_rcp_f32_e32 v69, v69
	v_exp_f32_e32 v76, v76
	v_exp_f32_e32 v77, v77
	v_and_b32_e32 v78, 0xffff0000, v133
	v_and_b32_e32 v82, 0xffff0000, v135
	v_lshlrev_b32_e32 v79, 16, v134
	v_mul_f32_e32 v73, v73, v69
	v_add_f32_e32 v69, 1.0, v76
	v_add_f32_e32 v76, 1.0, v77
	v_mul_f32_e32 v77, 0xbfb8aa3b, v78
	v_mul_f32_e32 v78, 0xbfb8aa3b, v82
	v_mul_f32_e32 v79, 0xbfb8aa3b, v79
	v_exp_f32_e32 v77, v77
	v_exp_f32_e32 v78, v78
	v_exp_f32_e32 v79, v79
	v_rcp_f32_e32 v69, v69
	v_add_f32_e32 v77, 1.0, v77
	v_add_f32_e32 v78, 1.0, v78
	v_add_f32_e32 v79, 1.0, v79
	v_rcp_f32_e32 v77, v77
	v_rcp_f32_e32 v78, v78
	v_rcp_f32_e32 v79, v79
	v_rcp_f32_e32 v76, v76
	v_mul_f32_e32 v69, v70, v69
	v_add_u32_e32 v104, 0x80, v152
	v_mul_f32_e32 v70, v71, v77
	v_mul_f32_e32 v71, v75, v78
	v_cvt_pk_bf16_f32 v68, v1, v68
	v_cvt_pk_bf16_f32 v69, v69, v70
	v_ashrrev_i32_e32 v105, 31, v104
	v_mul_f32_e32 v72, v72, v79
	v_mul_f32_e32 v74, v74, v76
	v_cvt_pk_bf16_f32 v70, v72, v73
	v_cvt_pk_bf16_f32 v71, v74, v71
	global_store_dwordx4 v[84:85], v[68:71], off offset:256
	v_add_u32_e32 v106, 0x90, v152
	v_ashrrev_i32_e32 v107, 31, v106
	v_lshlrev_b64 v[68:69], 12, v[104:105]
	v_lshl_add_u64 v[68:69], v[154:155], 0, v[68:69]
	global_load_dwordx4 v[92:95], v[68:69], off offset:2048
	global_load_dwordx4 v[96:99], v[68:69], off offset:2304
	v_lshlrev_b64 v[68:69], 12, v[106:107]
	v_lshl_add_u64 v[68:69], v[154:155], 0, v[68:69]
	global_load_dwordx4 v[100:103], v[68:69], off offset:2048
	global_load_dwordx4 v[84:87], v[68:69], off offset:2304
	v_add_u32_e32 v90, 0xa0, v152
	v_ashrrev_i32_e32 v91, 31, v90
	v_lshlrev_b64 v[68:69], 12, v[90:91]
	v_add_u32_e32 v88, 0xb0, v152
	v_lshl_add_u64 v[68:69], v[154:155], 0, v[68:69]
	v_ashrrev_i32_e32 v89, 31, v88
	global_load_dwordx4 v[80:83], v[68:69], off offset:2048
	global_load_dwordx4 v[76:79], v[68:69], off offset:2304
	v_lshlrev_b64 v[68:69], 12, v[88:89]
	v_lshl_add_u64 v[68:69], v[154:155], 0, v[68:69]
	v_lshlrev_b64 v[104:105], 11, v[104:105]
	global_load_dwordx4 v[72:75], v[68:69], off offset:2048
	s_nop 0
	global_load_dwordx4 v[68:71], v[68:69], off offset:2304
	v_lshl_add_u64 v[104:105], v[2:3], 0, v[104:105]
	s_waitcnt vmcnt(7)
	v_lshlrev_b32_e32 v1, 16, v92
	v_and_b32_e32 v92, 0xffff0000, v92
	v_mul_f32_e32 v1, 0xbfb8aa3b, v1
	v_mul_f32_e32 v92, 0xbfb8aa3b, v92
	v_exp_f32_e32 v1, v1
	v_exp_f32_e32 v92, v92
	v_lshlrev_b32_e32 v109, 16, v94
	v_and_b32_e32 v94, 0xffff0000, v94
	v_add_f32_e32 v1, 1.0, v1
	v_add_f32_e32 v92, 1.0, v92
	v_mul_f32_e32 v94, 0xbfb8aa3b, v94
	v_rcp_f32_e32 v1, v1
	v_rcp_f32_e32 v92, v92
	v_exp_f32_e32 v94, v94
	v_lshlrev_b32_e32 v108, 16, v93
	v_lshlrev_b32_e32 v110, 16, v95
	v_mul_f32_e32 v1, v60, v1
	v_mul_f32_e32 v60, v61, v92
	v_add_f32_e32 v61, 1.0, v94
	v_mul_f32_e32 v92, 0xbfb8aa3b, v108
	v_mul_f32_e32 v94, 0xbfb8aa3b, v110
	v_rcp_f32_e32 v61, v61
	v_exp_f32_e32 v92, v92
	v_exp_f32_e32 v94, v94
	v_and_b32_e32 v93, 0xffff0000, v93
	v_and_b32_e32 v95, 0xffff0000, v95
	v_mul_f32_e32 v65, v65, v61
	v_add_f32_e32 v61, 1.0, v92
	v_add_f32_e32 v92, 1.0, v94
	v_mul_f32_e32 v93, 0xbfb8aa3b, v93
	v_mul_f32_e32 v94, 0xbfb8aa3b, v95
	v_mul_f32_e32 v109, 0xbfb8aa3b, v109
	v_exp_f32_e32 v93, v93
	v_exp_f32_e32 v94, v94
	v_exp_f32_e32 v109, v109
	v_rcp_f32_e32 v61, v61
	v_add_f32_e32 v93, 1.0, v93
	v_add_f32_e32 v94, 1.0, v94
	v_add_f32_e32 v109, 1.0, v109
	v_rcp_f32_e32 v93, v93
	v_rcp_f32_e32 v94, v94
	v_rcp_f32_e32 v109, v109
	v_rcp_f32_e32 v92, v92
	v_mul_f32_e32 v61, v62, v61
	v_mul_f32_e32 v62, v63, v93
	v_mul_f32_e32 v63, v67, v94
	v_cvt_pk_bf16_f32 v60, v1, v60
	v_mul_f32_e32 v64, v64, v109
	v_mul_f32_e32 v66, v66, v92
	v_cvt_pk_bf16_f32 v61, v61, v62
	v_cvt_pk_bf16_f32 v62, v64, v65
	v_cvt_pk_bf16_f32 v63, v66, v63
	global_store_dwordx4 v[104:105], v[60:63], off
	s_waitcnt vmcnt(7)
	v_lshlrev_b32_e32 v1, 16, v96
	v_mul_f32_e32 v1, 0xbfb8aa3b, v1
	v_and_b32_e32 v60, 0xffff0000, v96
	v_mul_f32_e32 v60, 0xbfb8aa3b, v60
	v_exp_f32_e32 v1, v1
	v_exp_f32_e32 v60, v60
	v_and_b32_e32 v64, 0xffff0000, v98
	v_mul_f32_e32 v64, 0xbfb8aa3b, v64
	v_add_f32_e32 v1, 1.0, v1
	v_add_f32_e32 v60, 1.0, v60
	v_rcp_f32_e32 v1, v1
	v_rcp_f32_e32 v60, v60
	v_exp_f32_e32 v64, v64
	v_lshlrev_b32_e32 v61, 16, v97
	v_lshlrev_b32_e32 v65, 16, v99
	v_mul_f32_e32 v1, v52, v1
	v_mul_f32_e32 v52, v53, v60
	v_add_f32_e32 v53, 1.0, v64
	v_mul_f32_e32 v60, 0xbfb8aa3b, v61
	v_mul_f32_e32 v61, 0xbfb8aa3b, v65
	v_rcp_f32_e32 v53, v53
	v_exp_f32_e32 v60, v60
	v_exp_f32_e32 v61, v61
	v_and_b32_e32 v62, 0xffff0000, v97
	v_lshlrev_b32_e32 v63, 16, v98
	v_and_b32_e32 v66, 0xffff0000, v99
	v_mul_f32_e32 v57, v57, v53
	v_add_f32_e32 v53, 1.0, v60
	v_add_f32_e32 v60, 1.0, v61
	v_mul_f32_e32 v61, 0xbfb8aa3b, v62
	v_mul_f32_e32 v63, 0xbfb8aa3b, v63
	v_exp_f32_e32 v61, v61
	v_mul_f32_e32 v62, 0xbfb8aa3b, v66
	v_exp_f32_e32 v63, v63
	v_exp_f32_e32 v62, v62
	v_add_f32_e32 v61, 1.0, v61
	v_rcp_f32_e32 v53, v53
	v_add_f32_e32 v63, 1.0, v63
	v_rcp_f32_e32 v61, v61
	v_add_f32_e32 v62, 1.0, v62
	v_rcp_f32_e32 v63, v63
	v_rcp_f32_e32 v62, v62
	v_rcp_f32_e32 v60, v60
	v_mul_f32_e32 v53, v54, v53
	v_mul_f32_e32 v54, v55, v61
	v_mul_f32_e32 v56, v56, v63
	v_mul_f32_e32 v55, v59, v62
	v_cvt_pk_bf16_f32 v52, v1, v52
	v_cvt_pk_bf16_f32 v53, v53, v54
	v_cvt_pk_bf16_f32 v54, v56, v57
	v_mul_f32_e32 v58, v58, v60
	v_cvt_pk_bf16_f32 v55, v58, v55
	global_store_dwordx4 v[104:105], v[52:55], off offset:256
	s_waitcnt vmcnt(7)
	v_lshlrev_b32_e32 v1, 16, v100
	v_mul_f32_e32 v1, 0xbfb8aa3b, v1
	v_and_b32_e32 v54, 0xffff0000, v100
	v_mul_f32_e32 v54, 0xbfb8aa3b, v54
	v_exp_f32_e32 v1, v1
	v_exp_f32_e32 v54, v54
	v_and_b32_e32 v58, 0xffff0000, v102
	v_mul_f32_e32 v58, 0xbfb8aa3b, v58
	v_add_f32_e32 v1, 1.0, v1
	v_add_f32_e32 v54, 1.0, v54
	v_rcp_f32_e32 v1, v1
	v_rcp_f32_e32 v54, v54
	v_exp_f32_e32 v58, v58
	v_lshlrev_b32_e32 v55, 16, v101
	v_lshlrev_b32_e32 v59, 16, v103
	v_mul_f32_e32 v1, v44, v1
	v_mul_f32_e32 v44, v45, v54
	v_add_f32_e32 v45, 1.0, v58
	v_mul_f32_e32 v54, 0xbfb8aa3b, v55
	v_mul_f32_e32 v55, 0xbfb8aa3b, v59
	v_rcp_f32_e32 v45, v45
	v_exp_f32_e32 v54, v54
	v_exp_f32_e32 v55, v55
	v_and_b32_e32 v56, 0xffff0000, v101
	v_and_b32_e32 v60, 0xffff0000, v103
	v_lshlrev_b32_e32 v57, 16, v102
	v_mul_f32_e32 v49, v49, v45
	v_add_f32_e32 v45, 1.0, v54
	v_add_f32_e32 v54, 1.0, v55
	v_mul_f32_e32 v55, 0xbfb8aa3b, v56
	v_mul_f32_e32 v56, 0xbfb8aa3b, v60
	v_mul_f32_e32 v57, 0xbfb8aa3b, v57
	v_exp_f32_e32 v55, v55
	v_exp_f32_e32 v56, v56
	v_exp_f32_e32 v57, v57
	v_rcp_f32_e32 v45, v45
	v_add_f32_e32 v55, 1.0, v55
	v_add_f32_e32 v56, 1.0, v56
	v_add_f32_e32 v57, 1.0, v57
	v_rcp_f32_e32 v55, v55
	v_rcp_f32_e32 v56, v56
	v_rcp_f32_e32 v57, v57
	v_rcp_f32_e32 v54, v54
	v_lshlrev_b64 v[52:53], 11, v[106:107]
	v_lshl_add_u64 v[52:53], v[2:3], 0, v[52:53]
	v_mul_f32_e32 v45, v46, v45
	v_mul_f32_e32 v46, v47, v55
	v_mul_f32_e32 v47, v51, v56
	v_cvt_pk_bf16_f32 v44, v1, v44
	v_mul_f32_e32 v48, v48, v57
	v_mul_f32_e32 v50, v50, v54
	v_cvt_pk_bf16_f32 v45, v45, v46
	v_cvt_pk_bf16_f32 v46, v48, v49
	v_cvt_pk_bf16_f32 v47, v50, v47
	global_store_dwordx4 v[52:53], v[44:47], off
	s_waitcnt vmcnt(7)
	v_lshlrev_b32_e32 v1, 16, v84
	v_mul_f32_e32 v1, 0xbfb8aa3b, v1
	v_and_b32_e32 v44, 0xffff0000, v84
	v_mul_f32_e32 v44, 0xbfb8aa3b, v44
	v_exp_f32_e32 v1, v1
	v_exp_f32_e32 v44, v44
	v_and_b32_e32 v48, 0xffff0000, v86
	v_mul_f32_e32 v48, 0xbfb8aa3b, v48
	v_add_f32_e32 v1, 1.0, v1
	v_add_f32_e32 v44, 1.0, v44
	v_rcp_f32_e32 v1, v1
	v_rcp_f32_e32 v44, v44
	v_exp_f32_e32 v48, v48
	v_lshlrev_b32_e32 v45, 16, v85
	v_lshlrev_b32_e32 v49, 16, v87
	v_mul_f32_e32 v1, v36, v1
	v_mul_f32_e32 v36, v37, v44
	v_add_f32_e32 v37, 1.0, v48
	v_mul_f32_e32 v44, 0xbfb8aa3b, v45
	v_mul_f32_e32 v45, 0xbfb8aa3b, v49
	v_rcp_f32_e32 v37, v37
	v_exp_f32_e32 v44, v44
	v_exp_f32_e32 v45, v45
	v_and_b32_e32 v46, 0xffff0000, v85
	v_lshlrev_b32_e32 v47, 16, v86
	v_and_b32_e32 v50, 0xffff0000, v87
	v_mul_f32_e32 v41, v41, v37
	v_add_f32_e32 v37, 1.0, v44
	v_add_f32_e32 v44, 1.0, v45
	v_mul_f32_e32 v45, 0xbfb8aa3b, v46
	v_mul_f32_e32 v47, 0xbfb8aa3b, v47
	v_exp_f32_e32 v45, v45
	v_mul_f32_e32 v46, 0xbfb8aa3b, v50
	v_exp_f32_e32 v47, v47
	v_exp_f32_e32 v46, v46
	v_add_f32_e32 v45, 1.0, v45
	v_rcp_f32_e32 v37, v37
	v_add_f32_e32 v47, 1.0, v47
	v_rcp_f32_e32 v45, v45
	v_add_f32_e32 v46, 1.0, v46
	v_rcp_f32_e32 v47, v47
	v_rcp_f32_e32 v46, v46
	v_rcp_f32_e32 v44, v44
	v_mul_f32_e32 v37, v38, v37
	v_mul_f32_e32 v38, v39, v45
	v_mul_f32_e32 v40, v40, v47
	v_mul_f32_e32 v39, v43, v46
	v_cvt_pk_bf16_f32 v36, v1, v36
	v_cvt_pk_bf16_f32 v37, v37, v38
	v_cvt_pk_bf16_f32 v38, v40, v41
	v_mul_f32_e32 v42, v42, v44
	v_cvt_pk_bf16_f32 v39, v42, v39
	global_store_dwordx4 v[52:53], v[36:39], off offset:256
	s_waitcnt vmcnt(7)
	v_lshlrev_b32_e32 v1, 16, v80
	v_mul_f32_e32 v1, 0xbfb8aa3b, v1
	v_and_b32_e32 v38, 0xffff0000, v80
	v_mul_f32_e32 v38, 0xbfb8aa3b, v38
	v_exp_f32_e32 v1, v1
	v_exp_f32_e32 v38, v38
	v_and_b32_e32 v42, 0xffff0000, v82
	v_mul_f32_e32 v42, 0xbfb8aa3b, v42
	v_add_f32_e32 v1, 1.0, v1
	v_add_f32_e32 v38, 1.0, v38
	v_rcp_f32_e32 v1, v1
	v_rcp_f32_e32 v38, v38
	v_exp_f32_e32 v42, v42
	v_lshlrev_b32_e32 v39, 16, v81
	v_lshlrev_b32_e32 v43, 16, v83
	v_mul_f32_e32 v1, v28, v1
	v_mul_f32_e32 v28, v29, v38
	v_add_f32_e32 v29, 1.0, v42
	v_mul_f32_e32 v38, 0xbfb8aa3b, v39
	v_mul_f32_e32 v39, 0xbfb8aa3b, v43
	v_rcp_f32_e32 v29, v29
	v_exp_f32_e32 v38, v38
	v_exp_f32_e32 v39, v39
	v_and_b32_e32 v40, 0xffff0000, v81
	v_and_b32_e32 v44, 0xffff0000, v83
	v_lshlrev_b32_e32 v41, 16, v82
	v_mul_f32_e32 v33, v33, v29
	v_add_f32_e32 v29, 1.0, v38
	v_add_f32_e32 v38, 1.0, v39
	v_mul_f32_e32 v39, 0xbfb8aa3b, v40
	v_mul_f32_e32 v40, 0xbfb8aa3b, v44
	v_mul_f32_e32 v41, 0xbfb8aa3b, v41
	v_exp_f32_e32 v39, v39
	v_exp_f32_e32 v40, v40
	v_exp_f32_e32 v41, v41
	v_rcp_f32_e32 v29, v29
	v_add_f32_e32 v39, 1.0, v39
	v_add_f32_e32 v40, 1.0, v40
	v_add_f32_e32 v41, 1.0, v41
	v_rcp_f32_e32 v39, v39
	v_rcp_f32_e32 v40, v40
	v_rcp_f32_e32 v41, v41
	v_rcp_f32_e32 v38, v38
	v_lshlrev_b64 v[36:37], 11, v[90:91]
	v_lshl_add_u64 v[36:37], v[2:3], 0, v[36:37]
	v_mul_f32_e32 v29, v30, v29
	v_mul_f32_e32 v30, v31, v39
	v_mul_f32_e32 v31, v35, v40
	v_cvt_pk_bf16_f32 v28, v1, v28
	v_mul_f32_e32 v32, v32, v41
	v_mul_f32_e32 v34, v34, v38
	v_cvt_pk_bf16_f32 v29, v29, v30
	v_cvt_pk_bf16_f32 v30, v32, v33
	v_cvt_pk_bf16_f32 v31, v34, v31
	global_store_dwordx4 v[36:37], v[28:31], off
	s_waitcnt vmcnt(7)
	v_lshlrev_b32_e32 v1, 16, v76
	v_mul_f32_e32 v1, 0xbfb8aa3b, v1
	v_and_b32_e32 v28, 0xffff0000, v76
	v_mul_f32_e32 v28, 0xbfb8aa3b, v28
	v_exp_f32_e32 v1, v1
	v_exp_f32_e32 v28, v28
	v_and_b32_e32 v32, 0xffff0000, v78
	v_mul_f32_e32 v32, 0xbfb8aa3b, v32
	v_add_f32_e32 v1, 1.0, v1
	v_add_f32_e32 v28, 1.0, v28
	v_rcp_f32_e32 v1, v1
	v_rcp_f32_e32 v28, v28
	v_exp_f32_e32 v32, v32
	v_lshlrev_b32_e32 v29, 16, v77
	v_lshlrev_b32_e32 v33, 16, v79
	v_mul_f32_e32 v1, v20, v1
	v_mul_f32_e32 v20, v21, v28
	v_add_f32_e32 v21, 1.0, v32
	v_mul_f32_e32 v28, 0xbfb8aa3b, v29
	v_mul_f32_e32 v29, 0xbfb8aa3b, v33
	v_rcp_f32_e32 v21, v21
	v_exp_f32_e32 v28, v28
	v_exp_f32_e32 v29, v29
	v_and_b32_e32 v30, 0xffff0000, v77
	v_and_b32_e32 v34, 0xffff0000, v79
	v_lshlrev_b32_e32 v31, 16, v78
	v_mul_f32_e32 v25, v25, v21
	v_add_f32_e32 v21, 1.0, v28
	v_add_f32_e32 v28, 1.0, v29
	v_mul_f32_e32 v29, 0xbfb8aa3b, v30
	v_mul_f32_e32 v30, 0xbfb8aa3b, v34
	v_mul_f32_e32 v31, 0xbfb8aa3b, v31
	v_exp_f32_e32 v29, v29
	v_exp_f32_e32 v30, v30
	v_exp_f32_e32 v31, v31
	v_rcp_f32_e32 v21, v21
	v_add_f32_e32 v29, 1.0, v29
	v_add_f32_e32 v30, 1.0, v30
	v_add_f32_e32 v31, 1.0, v31
	v_rcp_f32_e32 v29, v29
	v_rcp_f32_e32 v30, v30
	v_rcp_f32_e32 v31, v31
	v_rcp_f32_e32 v28, v28
	v_mul_f32_e32 v21, v22, v21
	v_mul_f32_e32 v22, v23, v29
	v_mul_f32_e32 v23, v27, v30
	v_cvt_pk_bf16_f32 v20, v1, v20
	v_cvt_pk_bf16_f32 v21, v21, v22
	v_mul_f32_e32 v24, v24, v31
	v_mul_f32_e32 v26, v26, v28
	v_cvt_pk_bf16_f32 v22, v24, v25
	v_cvt_pk_bf16_f32 v23, v26, v23
	global_store_dwordx4 v[36:37], v[20:23], off offset:256
	s_waitcnt vmcnt(7)
	v_lshlrev_b32_e32 v1, 16, v72
	v_mul_f32_e32 v1, 0xbfb8aa3b, v1
	v_lshlrev_b64 v[20:21], 11, v[88:89]
	v_lshl_add_u64 v[20:21], v[2:3], 0, v[20:21]
	v_and_b32_e32 v2, 0xffff0000, v72
	v_mul_f32_e32 v2, 0xbfb8aa3b, v2
	v_exp_f32_e32 v1, v1
	v_exp_f32_e32 v2, v2
	v_and_b32_e32 v24, 0xffff0000, v74
	v_mul_f32_e32 v24, 0xbfb8aa3b, v24
	v_add_f32_e32 v1, 1.0, v1
	v_add_f32_e32 v2, 1.0, v2
	v_rcp_f32_e32 v1, v1
	v_rcp_f32_e32 v2, v2
	v_exp_f32_e32 v24, v24
	v_lshlrev_b32_e32 v25, 16, v75
	v_mul_f32_e32 v1, v12, v1
	v_mul_f32_e32 v2, v13, v2
	v_add_f32_e32 v12, 1.0, v24
	v_mul_f32_e32 v13, 0xbfb8aa3b, v25
	v_rcp_f32_e32 v12, v12
	v_exp_f32_e32 v13, v13
	v_and_b32_e32 v22, 0xffff0000, v73
	v_lshlrev_b32_e32 v3, 16, v73
	v_lshlrev_b32_e32 v23, 16, v74
	v_and_b32_e32 v26, 0xffff0000, v75
	v_mul_f32_e32 v17, v17, v12
	v_add_f32_e32 v12, 1.0, v13
	v_mul_f32_e32 v13, 0xbfb8aa3b, v22
	v_mul_f32_e32 v23, 0xbfb8aa3b, v23
	v_mul_f32_e32 v3, 0xbfb8aa3b, v3
	v_exp_f32_e32 v13, v13
	v_mul_f32_e32 v22, 0xbfb8aa3b, v26
	v_exp_f32_e32 v23, v23
	v_exp_f32_e32 v3, v3
	v_exp_f32_e32 v22, v22
	v_rcp_f32_e32 v12, v12
	v_add_f32_e32 v13, 1.0, v13
	v_add_f32_e32 v23, 1.0, v23
	v_add_f32_e32 v3, 1.0, v3
	v_rcp_f32_e32 v13, v13
	v_add_f32_e32 v22, 1.0, v22
	v_rcp_f32_e32 v23, v23
	v_rcp_f32_e32 v3, v3
	v_rcp_f32_e32 v22, v22
	v_mul_f32_e32 v18, v18, v12
	v_cvt_pk_bf16_f32 v12, v1, v2
	s_waitcnt vmcnt(6)
	v_and_b32_e32 v2, 0xffff0000, v68
	v_mul_f32_e32 v2, 0xbfb8aa3b, v2
	v_exp_f32_e32 v2, v2
	v_mul_f32_e32 v13, v15, v13
	v_mul_f32_e32 v16, v16, v23
	v_mul_f32_e32 v3, v14, v3
	v_mul_f32_e32 v15, v19, v22
	v_cvt_pk_bf16_f32 v13, v3, v13
	v_cvt_pk_bf16_f32 v14, v16, v17
	v_cvt_pk_bf16_f32 v15, v18, v15
	global_store_dwordx4 v[20:21], v[12:15], off
	v_lshlrev_b32_e32 v1, 16, v68
	v_mul_f32_e32 v1, 0xbfb8aa3b, v1
	v_lshlrev_b32_e32 v13, 16, v70
	v_and_b32_e32 v14, 0xffff0000, v70
	v_mul_f32_e32 v13, 0xbfb8aa3b, v13
	v_add_f32_e32 v2, 1.0, v2
	v_mul_f32_e32 v14, 0xbfb8aa3b, v14
	v_exp_f32_e32 v1, v1
	v_exp_f32_e32 v13, v13
	v_rcp_f32_e32 v2, v2
	v_exp_f32_e32 v14, v14
	v_add_f32_e32 v1, 1.0, v1
	v_add_f32_e32 v13, 1.0, v13
	v_mul_f32_e32 v2, v5, v2
	v_add_f32_e32 v5, 1.0, v14
	v_rcp_f32_e32 v1, v1
	v_rcp_f32_e32 v13, v13
	v_rcp_f32_e32 v5, v5
	v_lshlrev_b32_e32 v3, 16, v69
	v_and_b32_e32 v12, 0xffff0000, v69
	v_lshlrev_b32_e32 v15, 16, v71
	v_and_b32_e32 v16, 0xffff0000, v71
	v_mul_f32_e32 v3, 0xbfb8aa3b, v3
	v_mul_f32_e32 v1, v4, v1
	v_mul_f32_e32 v4, v8, v13
	v_exp_f32_e32 v3, v3
	v_mul_f32_e32 v8, 0xbfb8aa3b, v15
	v_mul_f32_e32 v5, v9, v5
	v_mul_f32_e32 v9, 0xbfb8aa3b, v12
	v_mul_f32_e32 v12, 0xbfb8aa3b, v16
	v_exp_f32_e32 v8, v8
	v_exp_f32_e32 v9, v9
	v_exp_f32_e32 v12, v12
	v_add_f32_e32 v3, 1.0, v3
	v_rcp_f32_e32 v3, v3
	v_add_f32_e32 v8, 1.0, v8
	v_add_f32_e32 v9, 1.0, v9
	v_add_f32_e32 v12, 1.0, v12
	v_rcp_f32_e32 v8, v8
	v_rcp_f32_e32 v9, v9
	v_rcp_f32_e32 v12, v12
	v_mul_f32_e32 v3, v6, v3
	v_mul_f32_e32 v6, v10, v8
	v_mul_f32_e32 v7, v7, v9
	v_mul_f32_e32 v8, v11, v12
	v_cvt_pk_bf16_f32 v2, v1, v2
	v_cvt_pk_bf16_f32 v3, v3, v7
	v_cvt_pk_bf16_f32 v4, v4, v5
	v_cvt_pk_bf16_f32 v5, v6, v8
	global_store_dwordx4 v[20:21], v[2:5], off offset:256
	s_cbranch_vccnz .LBB0_688
